# cross-attention softmax/P.V: exp+cvt per 16-key slice in place, interleaved between k-step-major P.V MFMAs, V fragments in two refilled banks (on top of the hoisted reads / unrolled QK)
# baseline (speedup 1.0000x reference)
; template <bool DIFF> ...
;     ...
;             f32x16 s0 = biasv, s1 = biasv;
;             LAS const unsigned char* ka = kb + l32 * KSTR + (DIFF ? c * 128 : 0) + hi * 16;
; #pragma unroll 1
;             for (int kq = 0; kq < NKS; kq += 4) {
;                 bf16x8 ka0[4], ka1[4], qq[4];
; #pragma unroll
;                 for (int j = 0; j < 4; ++j) {
;                     if (DIFF) { const int ko = 256 * l32 + 16 * (((c << 3) + 2 * j + hi) ^ (((l32 & 3) << 2) | ((l32 >> 2) & 3)));
;                         ka0[j] = *(LAS const bf16x8*)(kb + ko); ka1[j] = *(LAS const bf16x8*)(kb + 8192 + ko); }
;                     else { ka0[j] = *(LAS const bf16x8*)(ka + (kq + j) * 32); ka1[j] = *(LAS const bf16x8*)(ka + 32 * KSTR + (kq + j) * 32); }
;                     qq[j] = DIFF ? qf[DIFF ? j : 0] : *(LAS const bf16x8*)(qa + (kq + j) * 32); }
;                 __builtin_amdgcn_sched_barrier(0);
; #pragma unroll
;                 for (int j = 0; j < 4; ++j) { s0 = __builtin_amdgcn_mfma_f32_32x32x16_bf16(ka0[j], qq[j], s0, 0, 0, 0); s1 = __builtin_amdgcn_mfma_f32_32x32x16_bf16(ka1[j], qq[j], s1, 0, 0, 0); }
;             }
;             float c0 = 0.f, c1 = 0.f;
;             if (DIFF) {
;                 c0 = sl2 * (float)(64 * kt - wrow); c1 = sl2 * (float)(64 * kt + 32 - wrow);
;                 if (64 * kt + 64 > wrow) {
;                     asm volatile("" ::: "memory");
;                     const int irel = wrow + l32 - 64 * kt - hi * 4;
; #pragma unroll
;                     for (int r = 0; r < 16; ++r) { const int cr = (r >> 2) * 8 + (r & 3); if (cr > irel) s0[r] = -INFINITY; if (cr + 32 > irel) s1[r] = -INFINITY; }
;                 }
;             }
;             LAS const unsigned char* va = vb + (hi * 4 + ((lane & 15) >> 2)) * VSTR + (DIFF ? 0 : c * 256) + (((lane >> 4) & 1) * 16 + 4 * (lane & 3)) * 2;
;             bf16x8 fa[4], fb[4];
;             const int vq = (lane & 15) >> 2, vp = lane & 3, vg1 = (lane >> 4) & 1;
;             const int vs0 = 256 * (hi * 4 + vq) + 16 * ((2 * vg1 + (vp >> 1)) ^ hi) + 8 * (vp & 1), vs1 = 256 * (hi * 4 + 8 + vq) + 16 * ((2 * vg1 + (vp >> 1)) ^ (hi + 2)) + 8 * (vp & 1);
;     ...
;             float mx0 = s0[0], mx1 = s1[0];
; #pragma unroll
;             for (int r = 1; r < 16; r += 2) { mx0 = fmaxf(fmaxf(mx0, s0[r]), s0[r + 1 < 16 ? r + 1 : r]); mx1 = fmaxf(fmaxf(mx1, s1[r]), s1[r + 1 < 16 ? r + 1 : r]); }
.LBB0_255:
	v_add_u32_e32 v147, v201, v200
	v_add_u32_e32 v176, v206, v200
	v_add_u32_e32 v237, 0x11400, v176
	s_waitcnt lgkmcnt(0)
	s_barrier
	ds_read_b128 v[164:167], v237
	ds_read_b128 v[148:151], v147
	ds_read_b128 v[156:159], v147 offset:16896
	ds_read_b128 v[168:171], v237 offset:32
	ds_read_b128 v[152:155], v147 offset:32
	ds_read_b128 v[160:163], v147 offset:16928
	ds_read_b128 v[222:225], v237 offset:64
	ds_read_b128 v[172:175], v147 offset:64
	ds_read_b128 v[214:217], v147 offset:16960
	ds_read_b128 v[226:229], v237 offset:96
	ds_read_b128 v[210:213], v147 offset:96
	ds_read_b128 v[218:221], v147 offset:16992
	s_waitcnt lgkmcnt(9)
	v_mfma_f32_32x32x16_bf16 v[98:113], v[148:151], v[164:167], v[66:81]
	v_mfma_f32_32x32x16_bf16 v[82:97], v[156:159], v[164:167], v[66:81]
	s_waitcnt lgkmcnt(6)
	v_mfma_f32_32x32x16_bf16 v[98:113], v[152:155], v[168:171], v[98:113]
	v_mfma_f32_32x32x16_bf16 v[82:97], v[160:163], v[168:171], v[82:97]
	s_waitcnt lgkmcnt(3)
	v_mfma_f32_32x32x16_bf16 v[98:113], v[172:175], v[222:225], v[98:113]
	v_mfma_f32_32x32x16_bf16 v[82:97], v[214:217], v[222:225], v[82:97]
	s_waitcnt lgkmcnt(0)
	v_mfma_f32_32x32x16_bf16 v[98:113], v[210:213], v[226:229], v[98:113]
	v_mfma_f32_32x32x16_bf16 v[82:97], v[218:221], v[226:229], v[82:97]
	ds_read_b128 v[164:167], v237 offset:128
	ds_read_b128 v[148:151], v147 offset:128
	ds_read_b128 v[156:159], v147 offset:17024
	ds_read_b128 v[168:171], v237 offset:160
	ds_read_b128 v[152:155], v147 offset:160
	ds_read_b128 v[160:163], v147 offset:17056
	ds_read_b128 v[222:225], v237 offset:192
	ds_read_b128 v[172:175], v147 offset:192
	ds_read_b128 v[214:217], v147 offset:17088
	ds_read_b128 v[226:229], v237 offset:224
	ds_read_b128 v[210:213], v147 offset:224
	ds_read_b128 v[218:221], v147 offset:17120
	s_waitcnt lgkmcnt(9)
	v_mfma_f32_32x32x16_bf16 v[98:113], v[148:151], v[164:167], v[98:113]
	v_mfma_f32_32x32x16_bf16 v[82:97], v[156:159], v[164:167], v[82:97]
	s_waitcnt lgkmcnt(6)
	v_mfma_f32_32x32x16_bf16 v[98:113], v[152:155], v[168:171], v[98:113]
	v_mfma_f32_32x32x16_bf16 v[82:97], v[160:163], v[168:171], v[82:97]
	s_waitcnt lgkmcnt(3)
	v_mfma_f32_32x32x16_bf16 v[98:113], v[172:175], v[222:225], v[98:113]
	v_mfma_f32_32x32x16_bf16 v[82:97], v[214:217], v[222:225], v[82:97]
	s_waitcnt lgkmcnt(0)
	v_mfma_f32_32x32x16_bf16 v[98:113], v[210:213], v[226:229], v[98:113]
	v_mfma_f32_32x32x16_bf16 v[82:97], v[218:221], v[226:229], v[82:97]
	ds_read_b128 v[164:167], v237 offset:256
	ds_read_b128 v[148:151], v147 offset:256
	ds_read_b128 v[156:159], v147 offset:17152
	ds_read_b128 v[168:171], v237 offset:288
	ds_read_b128 v[152:155], v147 offset:288
	ds_read_b128 v[160:163], v147 offset:17184
	ds_read_b128 v[222:225], v237 offset:320
	ds_read_b128 v[172:175], v147 offset:320
	ds_read_b128 v[214:217], v147 offset:17216
	ds_read_b128 v[226:229], v237 offset:352
	ds_read_b128 v[210:213], v147 offset:352
	ds_read_b128 v[218:221], v147 offset:17248
	s_waitcnt lgkmcnt(9)
	v_mfma_f32_32x32x16_bf16 v[98:113], v[148:151], v[164:167], v[98:113]
	v_mfma_f32_32x32x16_bf16 v[82:97], v[156:159], v[164:167], v[82:97]
	s_waitcnt lgkmcnt(6)
	v_mfma_f32_32x32x16_bf16 v[98:113], v[152:155], v[168:171], v[98:113]
	v_mfma_f32_32x32x16_bf16 v[82:97], v[160:163], v[168:171], v[82:97]
	s_waitcnt lgkmcnt(3)
	v_mfma_f32_32x32x16_bf16 v[98:113], v[172:175], v[222:225], v[98:113]
	v_mfma_f32_32x32x16_bf16 v[82:97], v[214:217], v[222:225], v[82:97]
	s_waitcnt lgkmcnt(0)
	v_mfma_f32_32x32x16_bf16 v[98:113], v[210:213], v[226:229], v[98:113]
	v_mfma_f32_32x32x16_bf16 v[82:97], v[218:221], v[226:229], v[82:97]
	ds_read_b128 v[164:167], v237 offset:384
	ds_read_b128 v[148:151], v147 offset:384
	ds_read_b128 v[156:159], v147 offset:17280
	ds_read_b128 v[168:171], v237 offset:416
	ds_read_b128 v[152:155], v147 offset:416
	ds_read_b128 v[160:163], v147 offset:17312
	ds_read_b128 v[222:225], v237 offset:448
	ds_read_b128 v[172:175], v147 offset:448
	ds_read_b128 v[214:217], v147 offset:17344
	ds_read_b128 v[226:229], v237 offset:480
	ds_read_b128 v[210:213], v147 offset:480
	ds_read_b128 v[218:221], v147 offset:17376
	s_waitcnt lgkmcnt(9)
	v_mfma_f32_32x32x16_bf16 v[98:113], v[148:151], v[164:167], v[98:113]
	v_mfma_f32_32x32x16_bf16 v[82:97], v[156:159], v[164:167], v[82:97]
	s_waitcnt lgkmcnt(6)
	v_mfma_f32_32x32x16_bf16 v[98:113], v[152:155], v[168:171], v[98:113]
	v_mfma_f32_32x32x16_bf16 v[82:97], v[160:163], v[168:171], v[82:97]
	s_waitcnt lgkmcnt(3)
	v_mfma_f32_32x32x16_bf16 v[98:113], v[172:175], v[222:225], v[98:113]
	v_mfma_f32_32x32x16_bf16 v[82:97], v[214:217], v[222:225], v[82:97]
	s_waitcnt lgkmcnt(0)
	v_mfma_f32_32x32x16_bf16 v[98:113], v[210:213], v[226:229], v[98:113]
	v_mfma_f32_32x32x16_bf16 v[82:97], v[218:221], v[226:229], v[82:97]
	ds_read_b64_tr_b16 v[146:147], v205 offset:0
	ds_read_b64_tr_b16 v[148:149], v205 offset:4608
	ds_read_b64_tr_b16 v[150:151], v205 offset:64
	ds_read_b64_tr_b16 v[152:153], v205 offset:4672
	ds_read_b64_tr_b16 v[154:155], v205 offset:128
	ds_read_b64_tr_b16 v[156:157], v205 offset:4736
	ds_read_b64_tr_b16 v[158:159], v205 offset:192
	ds_read_b64_tr_b16 v[160:161], v205 offset:4800
	ds_read_b64_tr_b16 v[162:163], v205 offset:9216
	ds_read_b64_tr_b16 v[164:165], v205 offset:13824
	ds_read_b64_tr_b16 v[166:167], v205 offset:9280
	ds_read_b64_tr_b16 v[168:169], v205 offset:13888
	ds_read_b64_tr_b16 v[170:171], v205 offset:9344
	ds_read_b64_tr_b16 v[172:173], v205 offset:13952
	ds_read_b64_tr_b16 v[174:175], v205 offset:9408
	ds_read_b64_tr_b16 v[176:177], v205 offset:14016
	v_max3_f32 v0, v98, v99, v100
	v_max3_f32 v236, v82, v83, v84
	v_max3_f32 v0, v0, v101, v102
	v_max3_f32 v236, v236, v85, v86
	v_max3_f32 v0, v0, v103, v104
	v_max3_f32 v236, v236, v87, v88
	v_max3_f32 v0, v0, v105, v106
	v_max3_f32 v236, v236, v89, v90
	v_max3_f32 v0, v0, v107, v108
	v_max3_f32 v236, v236, v91, v92
	v_max3_f32 v0, v0, v109, v110
	v_max3_f32 v236, v236, v93, v94
	v_max3_f32 v0, v0, v111, v112
	v_max3_f32 v236, v236, v95, v96
	v_max_f32_e32 v0, v0, v113
	v_max_f32_e32 v236, v236, v97
	v_fma_f32 v0, v0, s44, 0
	v_fma_f32 v236, v236, s44, 0
	v_max_f32_e32 v0, v0, v236
	v_mov_b32_e32 v209, v0
	v_mov_b32_e32 v236, v0
	s_nop 1
	v_permlane32_swap_b32_e32 v209, v236
	s_nop 1
	v_max_f32_e32 v0, v209, v236
	v_cmp_gt_f32_e32 vcc, v0, v208
	s_cbranch_vccz .LBB0_252
; template <bool DIFF> ...
;     ...
;             if (__builtin_amdgcn_ballot_w64(mx > m_run) != 0ull) {
;                 const float mnew = fmaxf(m_run, mx), alpha = __builtin_amdgcn_exp2f(m_run - mnew); m_run = mnew; l_run *= alpha;
; #pragma unroll
;                 for (int i = 0; i < 4; ++i)
; #pragma unroll
;                     for (int r = 0; r < 16; ++r) o[i][r] *= alpha;
;             }
	v_max_f32_e32 v0, v0, v0
	v_max_f32_e32 v209, v208, v208
	v_max_f32_e32 v209, v209, v0
	v_sub_f32_e32 v0, v208, v209
	v_exp_f32_e32 v0, v0
	v_mov_b32_e32 v208, v209
	v_pk_mul_f32 v[64:65], v[64:65], v[0:1] op_sel_hi:[1,0]
	v_pk_mul_f32 v[62:63], v[62:63], v[0:1] op_sel_hi:[1,0]
	v_pk_mul_f32 v[60:61], v[60:61], v[0:1] op_sel_hi:[1,0]
	v_pk_mul_f32 v[58:59], v[58:59], v[0:1] op_sel_hi:[1,0]
	v_pk_mul_f32 v[56:57], v[56:57], v[0:1] op_sel_hi:[1,0]
	v_pk_mul_f32 v[54:55], v[54:55], v[0:1] op_sel_hi:[1,0]
	v_pk_mul_f32 v[52:53], v[52:53], v[0:1] op_sel_hi:[1,0]
	v_pk_mul_f32 v[50:51], v[50:51], v[0:1] op_sel_hi:[1,0]
	v_pk_mul_f32 v[48:49], v[48:49], v[0:1] op_sel_hi:[1,0]
	v_pk_mul_f32 v[46:47], v[46:47], v[0:1] op_sel_hi:[1,0]
	v_pk_mul_f32 v[44:45], v[44:45], v[0:1] op_sel_hi:[1,0]
	v_pk_mul_f32 v[42:43], v[42:43], v[0:1] op_sel_hi:[1,0]
	v_pk_mul_f32 v[40:41], v[40:41], v[0:1] op_sel_hi:[1,0]
	v_pk_mul_f32 v[38:39], v[38:39], v[0:1] op_sel_hi:[1,0]
	v_pk_mul_f32 v[36:37], v[36:37], v[0:1] op_sel_hi:[1,0]
	v_pk_mul_f32 v[34:35], v[34:35], v[0:1] op_sel_hi:[1,0]
	v_pk_mul_f32 v[32:33], v[32:33], v[0:1] op_sel_hi:[1,0]
	v_pk_mul_f32 v[30:31], v[30:31], v[0:1] op_sel_hi:[1,0]
	v_pk_mul_f32 v[28:29], v[28:29], v[0:1] op_sel_hi:[1,0]
	v_pk_mul_f32 v[26:27], v[26:27], v[0:1] op_sel_hi:[1,0]
	v_pk_mul_f32 v[24:25], v[24:25], v[0:1] op_sel_hi:[1,0]
	v_pk_mul_f32 v[22:23], v[22:23], v[0:1] op_sel_hi:[1,0]
	v_pk_mul_f32 v[20:21], v[20:21], v[0:1] op_sel_hi:[1,0]
	v_pk_mul_f32 v[18:19], v[18:19], v[0:1] op_sel_hi:[1,0]
	v_pk_mul_f32 v[16:17], v[16:17], v[0:1] op_sel_hi:[1,0]
	v_pk_mul_f32 v[14:15], v[14:15], v[0:1] op_sel_hi:[1,0]
	v_pk_mul_f32 v[12:13], v[12:13], v[0:1] op_sel_hi:[1,0]
	v_pk_mul_f32 v[10:11], v[10:11], v[0:1] op_sel_hi:[1,0]
	v_pk_mul_f32 v[8:9], v[8:9], v[0:1] op_sel_hi:[1,0]
	v_pk_mul_f32 v[6:7], v[6:7], v[0:1] op_sel_hi:[1,0]
	v_pk_mul_f32 v[4:5], v[4:5], v[0:1] op_sel_hi:[1,0]
	v_pk_mul_f32 v[2:3], v[2:3], v[0:1] op_sel_hi:[1,0]
	v_mul_f32_e32 v203, v203, v0
	s_branch .LBB0_252
